# FoX P.V sections: counted lgkmcnt(6/4/2/0) per MFMA instead of lgkmcnt(0) per 4-MFMA group
# speedup vs baseline: 1.0025x; 1.0025x over previous
; template <int VB>
; __device__ __forceinline__ void pv_tile(f32x16* o, int vb0, bf16x8 pa0, bf16x8 pa1, bf16x8 pa2, bf16x8 pa3) {
;     ...
;     PV_D0(0); PV_D0(1); PV_D0(2); PV_D0(3);
.LBB0_1180:
	s_add_i32 s35, s84, 1
	s_mul_hi_i32 s39, s35, 0x6000
	s_mulk_i32 s35, 0x6000
	s_add_u32 vcc_lo, s20, s35
	s_addc_u32 vcc_hi, s21, s39
	s_add_u32 s38, s22, s35
	s_addc_u32 s39, s23, s39
	v_lshl_add_u64 v[160:161], s[38:39], 0, v[176:177]
	s_waitcnt vmcnt(2)
	v_lshl_add_u64 v[164:165], s[38:39], 0, v[178:179]
	s_waitcnt vmcnt(1)
	v_lshl_add_u64 v[168:169], vcc, 0, v[176:177]
	s_waitcnt vmcnt(0)
	v_lshl_add_u64 v[172:173], vcc, 0, v[178:179]
	global_load_dwordx4 v[160:163], v[160:161], off
	s_nop 0
	global_load_dwordx4 v[164:167], v[164:165], off
	s_nop 0
	global_load_dwordx4 v[168:171], v[168:169], off
	s_nop 0
	global_load_dwordx4 v[172:175], v[172:173], off
	s_and_b64 vcc, exec, s[12:13]
	s_cbranch_vccnz .LBB0_1182
	ds_read_b64_tr_b16 v[208:209], v192 offset:0
	ds_read_b64_tr_b16 v[210:211], v192 offset:0x800
	ds_read_b64_tr_b16 v[212:213], v192 offset:0x1000
	ds_read_b64_tr_b16 v[214:215], v192 offset:0x1800
	ds_read_b64_tr_b16 v[216:217], v192 offset:0x2000
	ds_read_b64_tr_b16 v[218:219], v192 offset:0x2800
	ds_read_b64_tr_b16 v[220:221], v192 offset:0x3000
	ds_read_b64_tr_b16 v[222:223], v192 offset:0x3800
	s_waitcnt lgkmcnt(6)
	s_waitcnt vmcnt(7)
	v_mfma_f32_32x32x16_bf16 v[32:47], v[144:147], v[208:211], v[32:47]
	ds_read_b64_tr_b16 v[208:209], v192 offset:0x200
	ds_read_b64_tr_b16 v[210:211], v192 offset:0xa00
	s_waitcnt vmcnt(5)
	s_waitcnt lgkmcnt(6)
	v_mfma_f32_32x32x16_bf16 v[32:47], v[148:151], v[212:215], v[32:47]
	ds_read_b64_tr_b16 v[212:213], v192 offset:0x1200
	ds_read_b64_tr_b16 v[214:215], v192 offset:0x1a00
	s_waitcnt lgkmcnt(6)
	v_mfma_f32_32x32x16_bf16 v[32:47], v[152:155], v[216:219], v[32:47]
	ds_read_b64_tr_b16 v[216:217], v192 offset:0x2200
	ds_read_b64_tr_b16 v[218:219], v192 offset:0x2a00
	s_waitcnt vmcnt(4)
	s_waitcnt lgkmcnt(6)
	v_mfma_f32_32x32x16_bf16 v[32:47], v[156:159], v[220:223], v[32:47]
	ds_read_b64_tr_b16 v[220:221], v192 offset:0x3200
	ds_read_b64_tr_b16 v[222:223], v192 offset:0x3a00
	s_waitcnt lgkmcnt(6)
	v_mfma_f32_32x32x16_bf16 v[48:63], v[144:147], v[208:211], v[48:63]
	ds_read_b64_tr_b16 v[208:209], v192 offset:0x400
	ds_read_b64_tr_b16 v[210:211], v192 offset:0xc00
	s_waitcnt lgkmcnt(6)
	v_mfma_f32_32x32x16_bf16 v[48:63], v[148:151], v[212:215], v[48:63]
	ds_read_b64_tr_b16 v[212:213], v192 offset:0x1400
	ds_read_b64_tr_b16 v[214:215], v192 offset:0x1c00
	s_waitcnt lgkmcnt(6)
	v_mfma_f32_32x32x16_bf16 v[48:63], v[152:155], v[216:219], v[48:63]
	ds_read_b64_tr_b16 v[216:217], v192 offset:0x2400
	ds_read_b64_tr_b16 v[218:219], v192 offset:0x2c00
	s_waitcnt lgkmcnt(6)
	v_mfma_f32_32x32x16_bf16 v[48:63], v[156:159], v[220:223], v[48:63]
	ds_read_b64_tr_b16 v[220:221], v192 offset:0x3400
	ds_read_b64_tr_b16 v[222:223], v192 offset:0x3c00
	s_waitcnt lgkmcnt(6)
	v_mfma_f32_32x32x16_bf16 v[16:31], v[144:147], v[208:211], v[16:31]
	ds_read_b64_tr_b16 v[208:209], v192 offset:0x600
	ds_read_b64_tr_b16 v[210:211], v192 offset:0xe00
	s_waitcnt lgkmcnt(6)
	v_mfma_f32_32x32x16_bf16 v[16:31], v[148:151], v[212:215], v[16:31]
	ds_read_b64_tr_b16 v[212:213], v192 offset:0x1600
	ds_read_b64_tr_b16 v[214:215], v192 offset:0x1e00
	s_waitcnt lgkmcnt(6)
	v_mfma_f32_32x32x16_bf16 v[16:31], v[152:155], v[216:219], v[16:31]
	ds_read_b64_tr_b16 v[216:217], v192 offset:0x2600
	ds_read_b64_tr_b16 v[218:219], v192 offset:0x2e00
	s_waitcnt lgkmcnt(6)
	v_mfma_f32_32x32x16_bf16 v[16:31], v[156:159], v[220:223], v[16:31]
	ds_read_b64_tr_b16 v[220:221], v192 offset:0x3600
	ds_read_b64_tr_b16 v[222:223], v192 offset:0x3e00
	s_waitcnt lgkmcnt(6)
	v_mfma_f32_32x32x16_bf16 v[0:15], v[144:147], v[208:211], v[0:15]
	s_waitcnt lgkmcnt(4)
	v_mfma_f32_32x32x16_bf16 v[0:15], v[148:151], v[212:215], v[0:15]
	s_waitcnt lgkmcnt(2)
	v_mfma_f32_32x32x16_bf16 v[0:15], v[152:155], v[216:219], v[0:15]
	s_waitcnt lgkmcnt(0)
	v_mfma_f32_32x32x16_bf16 v[0:15], v[156:159], v[220:223], v[0:15]

; template <int VB>
; __device__ __forceinline__ void pv_tile(f32x16* o, int vb0, bf16x8 pa0, bf16x8 pa1, bf16x8 pa2, bf16x8 pa3) {
;     ...
;     PV_D0(0); PV_D0(1); PV_D0(2); PV_D0(3);
.LBB0_1199:
	ds_read_b64_tr_b16 v[208:209], v192 offset:0x4000
	ds_read_b64_tr_b16 v[210:211], v192 offset:0x4800
	ds_read_b64_tr_b16 v[212:213], v192 offset:0x5000
	ds_read_b64_tr_b16 v[214:215], v192 offset:0x5800
	ds_read_b64_tr_b16 v[216:217], v192 offset:0x6000
	ds_read_b64_tr_b16 v[218:219], v192 offset:0x6800
	ds_read_b64_tr_b16 v[220:221], v192 offset:0x7000
	ds_read_b64_tr_b16 v[222:223], v192 offset:0x7800
	s_waitcnt lgkmcnt(6)
	s_nop 0
	v_mfma_f32_32x32x16_bf16 v[32:47], v[144:147], v[208:211], v[32:47]
	ds_read_b64_tr_b16 v[208:209], v192 offset:0x4200
	ds_read_b64_tr_b16 v[210:211], v192 offset:0x4a00
	s_waitcnt lgkmcnt(6)
	v_mfma_f32_32x32x16_bf16 v[32:47], v[148:151], v[212:215], v[32:47]
	ds_read_b64_tr_b16 v[212:213], v192 offset:0x5200
	ds_read_b64_tr_b16 v[214:215], v192 offset:0x5a00
	s_waitcnt lgkmcnt(6)
	v_mfma_f32_32x32x16_bf16 v[32:47], v[152:155], v[216:219], v[32:47]
	ds_read_b64_tr_b16 v[216:217], v192 offset:0x6200
	ds_read_b64_tr_b16 v[218:219], v192 offset:0x6a00
	s_waitcnt lgkmcnt(6)
	v_mfma_f32_32x32x16_bf16 v[32:47], v[156:159], v[220:223], v[32:47]
	ds_read_b64_tr_b16 v[220:221], v192 offset:0x7200
	ds_read_b64_tr_b16 v[222:223], v192 offset:0x7a00
	s_waitcnt lgkmcnt(6)
	v_mfma_f32_32x32x16_bf16 v[48:63], v[144:147], v[208:211], v[48:63]
	ds_read_b64_tr_b16 v[208:209], v192 offset:0x4400
	ds_read_b64_tr_b16 v[210:211], v192 offset:0x4c00
	s_waitcnt lgkmcnt(6)
	v_mfma_f32_32x32x16_bf16 v[48:63], v[148:151], v[212:215], v[48:63]
	ds_read_b64_tr_b16 v[212:213], v192 offset:0x5400
	ds_read_b64_tr_b16 v[214:215], v192 offset:0x5c00
	s_waitcnt lgkmcnt(6)
	v_mfma_f32_32x32x16_bf16 v[48:63], v[152:155], v[216:219], v[48:63]
	ds_read_b64_tr_b16 v[216:217], v192 offset:0x6400
	ds_read_b64_tr_b16 v[218:219], v192 offset:0x6c00
	s_waitcnt lgkmcnt(6)
	v_mfma_f32_32x32x16_bf16 v[48:63], v[156:159], v[220:223], v[48:63]
	ds_read_b64_tr_b16 v[220:221], v192 offset:0x7400
	ds_read_b64_tr_b16 v[222:223], v192 offset:0x7c00
	s_waitcnt lgkmcnt(6)
	v_mfma_f32_32x32x16_bf16 v[16:31], v[144:147], v[208:211], v[16:31]
	ds_read_b64_tr_b16 v[208:209], v192 offset:0x4600
	ds_read_b64_tr_b16 v[210:211], v192 offset:0x4e00
	s_waitcnt lgkmcnt(6)
	v_mfma_f32_32x32x16_bf16 v[16:31], v[148:151], v[212:215], v[16:31]
	ds_read_b64_tr_b16 v[212:213], v192 offset:0x5600
	ds_read_b64_tr_b16 v[214:215], v192 offset:0x5e00
	s_waitcnt lgkmcnt(6)
	v_mfma_f32_32x32x16_bf16 v[16:31], v[152:155], v[216:219], v[16:31]
	ds_read_b64_tr_b16 v[216:217], v192 offset:0x6600
	ds_read_b64_tr_b16 v[218:219], v192 offset:0x6e00
	s_waitcnt lgkmcnt(6)
	v_mfma_f32_32x32x16_bf16 v[16:31], v[156:159], v[220:223], v[16:31]
	ds_read_b64_tr_b16 v[220:221], v192 offset:0x7600
	ds_read_b64_tr_b16 v[222:223], v192 offset:0x7e00
	s_waitcnt lgkmcnt(6)
	v_mfma_f32_32x32x16_bf16 v[0:15], v[144:147], v[208:211], v[0:15]
	s_waitcnt lgkmcnt(4)
	v_mfma_f32_32x32x16_bf16 v[0:15], v[148:151], v[212:215], v[0:15]
	s_waitcnt lgkmcnt(2)
	v_mfma_f32_32x32x16_bf16 v[0:15], v[152:155], v[216:219], v[0:15]
	s_waitcnt lgkmcnt(0)
	v_mfma_f32_32x32x16_bf16 v[0:15], v[156:159], v[220:223], v[0:15]
	s_and_b64 vcc, exec, s[12:13]
	s_cbranch_vccnz .LBB0_1203
